# P3 DFT half: W_down conversion runs first (HBM idle while the other half is VALU-bound) instead of last; rest as v058
# baseline (speedup 1.0000x reference)
.LBB0_2:
	s_or_b64 exec, exec, s[4:5]
	s_waitcnt lgkmcnt(0)
	s_mov_b32 s98, 0
	v_writelane_b32 v255, s98, 7
	s_add_u32 s36, s66, 0x40000
	s_addc_u32 s37, s67, 0
	s_lshl_b32 s78, s2, 9
	v_add_u32_e32 v64, s78, v66
	s_movk_i32 s6, 0xd80
	s_getreg_b32 s20, hwreg(HW_REG_XCC_ID, 0, 4)
	v_cmp_gt_i32_e64 s[4:5], s6, v64
	s_and_saveexec_b64 s[10:11], s[4:5]
	s_cbranch_execz .LBB0_10
	s_lshl_b32 s12, s3, 9
	v_cvt_f32_u32_e32 v1, s12
	v_add_u32_e32 v65, s12, v64
	v_mov_b32_e32 v2, s12
	v_cmp_gt_i32_e64 s[4:5], s6, v65
	v_rcp_iflag_f32_e32 v1, v1
	s_sub_i32 s13, 0, s12
	v_max_i32_e32 v3, 0xd80, v65
	v_addc_co_u32_e64 v2, s[6:7], v64, v2, s[4:5]
	v_mul_f32_e32 v1, 0x4f7ffffe, v1
	v_cvt_u32_f32_e32 v1, v1
	v_sub_u32_e32 v2, v3, v2
	s_mov_b64 s[14:15], -1
	v_mul_lo_u32 v3, s13, v1
	v_mul_hi_u32 v3, v1, v3
	v_add_u32_e32 v1, v1, v3
	v_mul_hi_u32 v1, v2, v1
	v_mul_lo_u32 v3, v1, s12
	v_sub_u32_e32 v2, v2, v3
	v_add_u32_e32 v4, 1, v1
	v_cmp_le_u32_e64 s[6:7], s12, v2
	v_subrev_u32_e32 v3, s12, v2
	s_nop 0
	v_cndmask_b32_e64 v1, v1, v4, s[6:7]
	v_cndmask_b32_e64 v2, v2, v3, s[6:7]
	v_add_u32_e32 v3, 1, v1
	v_cmp_le_u32_e64 s[6:7], s12, v2
	v_mov_b32_e32 v2, v64
	s_nop 0
	v_cndmask_b32_e64 v1, v1, v3, s[6:7]
	v_addc_co_u32_e64 v1, s[4:5], 1, v1, s[4:5]
	v_cmp_lt_u32_e64 s[4:5], 1, v1
	s_and_saveexec_b64 s[6:7], s[4:5]
	s_cbranch_execz .LBB0_7
	v_and_b32_e32 v4, -2, v1
	s_lshl_b32 s13, s3, 10
	s_mov_b32 s16, s13
	s_mov_b64 s[14:15], 0
	v_mov_b32_e32 v5, 0
	v_mov_b32_e32 v6, v4
	v_mov_b64_e32 v[2:3], v[64:65]

.LBB0_286:
	s_mov_b32 s82, s37
	s_mov_b32 s77, s36
	v_readlane_b32 s36, v254, 14
	s_and_b64 vcc, exec, s[0:1]
	s_mov_b64 s[78:79], s[42:43]
	v_readlane_b32 s37, v254, 15
	v_readlane_b32 s83, v254, 27
	s_cbranch_vccz .LBB0_340
	s_mov_b32 s98, s8
	s_mov_b32 s99, s9
	s_mov_b32 s100, s10
	s_mov_b32 s101, s11
	s_mov_b32 s0, 1
	v_writelane_b32 v255, s0, 7
	s_branch .LBB0_333
.Lcf_dft_start:
	v_readlane_b32 s0, v254, 3
	s_lshl_b32 s0, s0, 5
	s_and_b32 s20, s0, 0x60
	s_lshr_b32 s58, s20, 3
	s_cmpk_lt_i32 s2, 0x80
	s_cselect_b64 s[4:5], -1, 0
	s_lshl_b32 s0, s2, 2
	s_and_b32 s0, s0, 28
	s_ashr_i32 s59, s2, 5
	s_add_i32 s12, s0, s59
	s_bfe_u32 s56, s2, 0x20003
	s_cmpk_gt_i32 s2, 0x7f
	v_mbcnt_lo_u32_b32 v14, -1, 0
	v_mbcnt_hi_u32_b32 v14, -1, v14
	s_cbranch_scc1 .LBB0_303
	v_lshl_add_u32 v0, v14, 4, s40
	v_add_u32_e32 v1, 0x2000, v0
	v_ashrrev_i32_e32 v2, 31, v1
	v_lshrrev_b32_e32 v2, 22, v2
	v_add_u32_e32 v2, v1, v2
	v_ashrrev_i32_e32 v8, 10, v2
	v_mul_i32_i24_e32 v2, 0x400, v8
	v_sub_u32_e32 v1, v1, v2
	v_lshrrev_b32_e32 v2, 4, v1
	v_bitop3_b32 v1, v2, v1, 32 bitop3:0x6c
	v_ashrrev_i32_e32 v2, 31, v1
	v_lshrrev_b32_e32 v2, 26, v2
	v_add_u32_e32 v2, v1, v2
	v_ashrrev_i32_e32 v9, 6, v2
	v_lshlrev_b32_e32 v3, 3, v8
	v_and_b32_e32 v2, 0xffc0, v2
	v_and_b32_e32 v3, -16, v3
	v_sub_u32_e32 v1, v1, v2
	v_readlane_b32 s0, v254, 17
	v_add_u32_e32 v3, v9, v3
	v_lshrrev_b16_e32 v2, 7, v1
	s_mov_b32 m0, s0
	v_and_b32_e32 v4, 3, v9
	s_mov_b32 s0, 0xfffe0
	v_lshrrev_b32_e32 v5, 2, v3
	v_lshlrev_b32_e32 v6, 1, v3
	v_and_b32_e32 v2, 1, v2
	v_and_or_b32 v4, v3, s0, v4
	v_and_b32_e32 v5, 4, v5
	v_and_b32_e32 v6, 24, v6
	v_add_u16_e32 v1, v1, v2
	v_mov_b32_e32 v2, 1
	v_or3_b32 v4, v4, v5, v6
	v_lshlrev_b32_e32 v5, 5, v8
	v_ashrrev_i16_sdwa v1, v2, sext(v1) dst_sel:DWORD dst_unused:UNUSED_PAD src0_sel:DWORD src1_sel:BYTE_0
	v_and_b32_e32 v5, 32, v5
	s_waitcnt lgkmcnt(0)
	v_bfe_i32 v10, v1, 0, 16
	v_add_lshl_u32 v1, v5, v10, 1
	v_lshl_add_u32 v128, v4, 12, v1
	v_lshl_add_u32 v130, v3, 12, v1
	v_ashrrev_i32_e32 v1, 31, v0
	v_lshrrev_b32_e32 v1, 22, v1
	v_add_u32_e32 v1, v0, v1
	v_ashrrev_i32_e32 v11, 10, v1
	v_mul_i32_i24_e32 v1, 0x400, v11
	v_sub_u32_e32 v0, v0, v1
	v_lshrrev_b32_e32 v1, 4, v0
	v_bitop3_b32 v0, v1, v0, 32 bitop3:0x6c
	v_ashrrev_i32_e32 v1, 31, v0
	v_lshrrev_b32_e32 v1, 26, v1
	v_add_u32_e32 v1, v0, v1
	v_lshlrev_b32_e32 v3, 3, v11
	v_ashrrev_i32_e32 v12, 6, v1
	v_and_b32_e32 v3, -16, v3
	v_add_u32_e32 v3, v12, v3
	v_and_b32_e32 v4, 3, v12
	s_ashr_i32 s13, s12, 31
	v_and_or_b32 v4, v3, s0, v4
	v_lshrrev_b32_e32 v5, 2, v3
	v_lshlrev_b32_e32 v6, 1, v3
	v_and_b32_e32 v1, 0xc0, v1
	s_lshl_b32 s14, s56, 20
	s_lshl_b64 s[0:1], s[12:13], 20
	v_and_b32_e32 v5, 4, v5
	v_and_b32_e32 v6, 24, v6
	v_sub_u32_e32 v0, v0, v1
	s_add_u32 s0, s10, s0
	v_or3_b32 v4, v4, v5, v6
	v_lshlrev_b32_e32 v5, 5, v11
	v_ashrrev_i16_sdwa v0, v2, sext(v0) dst_sel:DWORD dst_unused:UNUSED_PAD src0_sel:DWORD src1_sel:BYTE_0
	s_addc_u32 s1, s11, s1
	s_lshl_b32 s13, s56, 10
	v_and_b32_e32 v5, 32, v5
	v_bfe_i32 v13, v0, 0, 16
	s_and_b32 s13, s13, 0x800
	v_add_lshl_u32 v0, v5, v13, 1
	s_add_u32 s52, s0, s13
	v_lshl_add_u32 v132, v4, 12, v0
	s_addc_u32 s53, s1, 0
	v_readlane_b32 s0, v254, 18
	global_load_lds_dwordx4 v132, s[52:53]
	s_mov_b32 m0, s0
	s_add_u32 s0, s52, 0x80000
	v_readlane_b32 s6, v254, 19
	global_load_lds_dwordx4 v128, s[52:53]
	s_addc_u32 s1, s53, 0
	s_mov_b32 m0, s6
	v_readlane_b32 s6, v254, 20
	global_load_lds_dwordx4 v132, s[0:1]
	s_mov_b32 m0, s6
	s_add_u32 s50, s8, s14
	v_lshl_add_u32 v134, v3, 12, v0
	global_load_lds_dwordx4 v128, s[0:1]
	s_addc_u32 s51, s9, 0
	s_mov_b32 m0, s33
	s_add_u32 s0, s50, 0x80000
	global_load_lds_dwordx4 v134, s[50:51]
	s_mov_b32 m0, s88
	s_addc_u32 s1, s51, 0
	global_load_lds_dwordx4 v130, s[50:51]
	s_mov_b32 m0, s89
	v_readlane_b32 s6, v254, 21
	global_load_lds_dwordx4 v134, s[0:1]
	s_mov_b32 m0, s90
	v_mov_b32_e32 v133, 0
	global_load_lds_dwordx4 v130, s[0:1]
	v_readlane_b32 s7, v254, 22
	v_mov_b32_e32 v129, v133
	v_mov_b32_e32 v135, v133
	v_mov_b32_e32 v131, v133
	v_cndmask_b32_e64 v4, 0, 1, s[6:7]
	s_mov_b32 s63, 0
	v_lshl_add_u64 v[6:7], s[52:53], 0, v[132:133]
	v_lshl_add_u64 v[2:3], s[52:53], 0, v[128:129]
	v_lshl_add_u64 v[0:1], s[50:51], 0, v[134:135]
	v_cmp_ne_u32_e64 s[0:1], 1, v4
	s_andn2_b64 vcc, exec, s[6:7]
	v_lshl_add_u64 v[4:5], s[50:51], 0, v[130:131]
	s_cbranch_vccnz .LBB0_290
	s_barrier

.LBB0_333:
	v_readlane_b32 s0, v255, 7
	s_nop 3
	s_cmp_eq_u32 s0, 2
	s_cbranch_scc1 .LBB0_340
	s_cmpk_gt_i32 s24, 0xfff
	v_mbcnt_lo_u32_b32 v166, -1, 0
	v_mbcnt_hi_u32_b32 v166, -1, v166
	s_cbranch_scc1 .LBB0_340
	v_ashrrev_i32_e32 v1, 3, v166
	v_or_b32_e32 v4, 1, v1
	v_and_b32_e32 v2, -2, v1
	v_ashrrev_i32_e32 v5, 31, v4
	v_lshlrev_b64 v[132:133], 11, v[4:5]
	v_add_u32_e32 v4, 9, v2
	v_ashrrev_i32_e32 v5, 31, v4
	v_ashrrev_i32_e32 v3, 31, v2
	v_lshlrev_b64 v[136:137], 11, v[4:5]
	v_add_u32_e32 v4, 17, v2
	v_lshlrev_b64 v[130:131], 11, v[2:3]
	s_mov_b64 s[0:1], 0x4000
	v_ashrrev_i32_e32 v5, 31, v4
	v_lshl_add_u64 v[134:135], v[130:131], 0, s[0:1]
	s_mov_b64 s[0:1], 0x8000
	v_lshlrev_b64 v[140:141], 11, v[4:5]
	v_add_u32_e32 v4, 25, v2
	v_lshl_add_u64 v[138:139], v[130:131], 0, s[0:1]
	s_mov_b64 s[0:1], 0xc000
	v_ashrrev_i32_e32 v5, 31, v4
	v_lshl_add_u64 v[142:143], v[130:131], 0, s[0:1]
	v_lshlrev_b64 v[144:145], 11, v[4:5]
	s_mov_b64 s[0:1], 0x10000
	v_add_u32_e32 v4, 33, v2
	v_lshl_add_u64 v[146:147], v[130:131], 0, s[0:1]
	v_ashrrev_i32_e32 v5, 31, v4
	s_mov_b64 s[0:1], 0x14000
	v_lshlrev_b64 v[148:149], 11, v[4:5]
	v_lshl_add_u64 v[150:151], v[130:131], 0, s[0:1]
	v_add_u32_e32 v4, 41, v2
	s_mov_b64 s[0:1], 0x18000
	v_lshlrev_b32_e32 v0, 2, v166
	v_ashrrev_i32_e32 v5, 31, v4
	v_lshl_add_u64 v[154:155], v[130:131], 0, s[0:1]
	s_mov_b64 s[0:1], 0x1c000
	v_and_b32_e32 v0, 60, v0
	v_lshlrev_b64 v[152:153], 11, v[4:5]
	v_add_u32_e32 v4, 49, v2
	v_lshl_add_u64 v[158:159], v[130:131], 0, s[0:1]
	v_add_u32_e32 v2, 57, v2
	v_readlane_b32 s0, v254, 3
	v_mov_b32_e32 v129, 0
	v_ashrrev_i32_e32 v5, 31, v4
	v_ashrrev_i32_e32 v3, 31, v2
	s_lshl_b32 s0, s0, 6
	v_readlane_b32 s1, v254, 13
	v_lshlrev_b32_e32 v162, 2, v0
	s_lshl_b32 s8, s57, 3
	v_lshlrev_b64 v[156:157], 11, v[4:5]
	v_lshlrev_b64 v[160:161], 11, v[2:3]
	s_lshl_b32 s9, s57, 4
	s_lshl_b32 s10, s57, 9
	s_add_i32 s11, s1, s0
	s_lshl_b32 s12, s57, 10
	v_mov_b32_e32 v164, v162
	v_mov_b32_e32 v165, v129
	s_movk_i32 s13, 0x70
	s_movk_i32 s14, 0x50
	s_movk_i32 s15, 0x60
	s_branch .LBB0_336

.LBB0_340:
	v_readlane_b32 s0, v255, 7
	s_nop 3
	s_cmp_lg_u32 s0, 1
	s_cbranch_scc1 .Lcf_join
	s_mov_b32 s0, 2
	v_writelane_b32 v255, s0, 7
	s_mov_b32 s8, s98
	s_mov_b32 s9, s99
	s_mov_b32 s10, s100
	s_mov_b32 s11, s101
	s_waitcnt lgkmcnt(0)
	s_barrier
	s_branch .Lcf_dft_start
